# grid barrier: all waiters poll the top-level arrival counter (count >= (gen+1)*nx) instead of the generation word bumped afterwards by the last arriver; one atomic hop less per barrier, fences unchang
# speedup vs baseline: 1.0047x; 1.0047x over previous
; DI unsigned xb_ld(unsigned* p) { return __hip_atomic_load(p, __ATOMIC_RELAXED, __HIP_MEMORY_SCOPE_AGENT); }
; DI unsigned xb_add(unsigned* p, unsigned v) { return __hip_atomic_fetch_add(p, v, __ATOMIC_RELAXED, __HIP_MEMORY_SCOPE_AGENT); }
; #define XB_SPIN(cond, bar) do { unsigned _sp = 0; while (cond) { __builtin_amdgcn_s_sleep(1); \
;     if ((++_sp & 255u) == 0u) { if (xb_ld(&(bar)[XB_TMO])) break; if (_sp > XB_SPIN_CAP) { atomicAdd(&(bar)[XB_TMO], 1u); break; } } } } while (0)
; DI void xcd_barrier(const XcdBarrier& b) {
;     ...
;     const unsigned old = xb_add(&bar[XB_XSUB(b.x)], 1u);
;     const unsigned gen = old / nloc;
;     if (old + 1u == (gen + 1u) * nloc) {
;       __builtin_amdgcn_fence(__ATOMIC_RELEASE, "agent");
;       asm volatile("s_waitcnt vmcnt(0)" ::: "memory");
;       const unsigned og = xb_add(&bar[XB_TOP], 1u);
;       const unsigned tg = og / nx;
;       if (og + 1u == (tg + 1u) * nx) xb_add(&bar[XB_TOPGEN], 1u);
;       else XB_SPIN(xb_ld(&bar[XB_TOPGEN]) == tg, bar);
;       __builtin_amdgcn_fence(__ATOMIC_ACQUIRE, "agent");
;       xb_add(&bar[XB_XGEN(b.x)], 1u);
;       asm volatile("s_waitcnt vmcnt(0)" ::: "memory");
;     } else {
;       XB_SPIN(xb_ld(&bar[XB_XGEN(b.x)]) == gen, bar);
.LBB0_72:
	s_or_b64 exec, exec, s[4:5]
	v_cvt_f32_u32_e32 v4, v2
	s_waitcnt vmcnt(0)
	v_readfirstlane_b32 s3, v3
	v_rcp_iflag_f32_e32 v4, v4
	s_nop 0
	v_add_u32_e32 v1, s3, v1
	v_add_u32_e32 v5, 1, v1
	v_mul_f32_e32 v3, 0x4f7ffffe, v4
	v_cvt_u32_f32_e32 v3, v3
	v_sub_u32_e32 v4, 0, v2
	v_mul_lo_u32 v4, v4, v3
	v_mul_hi_u32 v4, v3, v4
	v_add_u32_e32 v3, v3, v4
	v_mul_hi_u32 v3, v1, v3
	v_mul_lo_u32 v4, v3, v2
	v_sub_u32_e32 v1, v1, v4
	v_add_u32_e32 v6, 1, v3
	v_cmp_ge_u32_e32 vcc, v1, v2
	v_sub_u32_e32 v4, v1, v2
	s_nop 0
	v_cndmask_b32_e32 v3, v3, v6, vcc
	v_cndmask_b32_e32 v1, v1, v4, vcc
	v_add_u32_e32 v4, 1, v3
	v_cmp_ge_u32_e32 vcc, v1, v2
	s_nop 1
	v_cndmask_b32_e32 v1, v3, v4, vcc
	v_mad_u64_u32 v[2:3], s[4:5], v2, v1, v[2:3]
	v_cmp_ne_u32_e32 vcc, v5, v2
	s_and_saveexec_b64 s[4:5], vcc
	s_xor_b64 s[4:5], exec, s[4:5]
	s_cbranch_execz .LBB0_86
	v_readlane_b32 s6, v251, 55
	s_waitcnt lgkmcnt(0)
	v_mad_u32_u24 v4, v1, v0, v0
	v_mov_b32_e32 v0, 0
	v_readlane_b32 s7, v251, 56
	s_nop 4
	global_load_dword v2, v0, s[6:7] sc1
	s_waitcnt vmcnt(0)
	v_cmp_lt_u32_e32 vcc, v2, v4
	s_and_saveexec_b64 s[6:7], vcc
	s_cbranch_execz .LBB0_85
	s_mov_b32 s3, 1
	s_mov_b64 s[8:9], 0
	s_branch .LBB0_76

; DI unsigned xb_ld(unsigned* p) { return __hip_atomic_load(p, __ATOMIC_RELAXED, __HIP_MEMORY_SCOPE_AGENT); }
; #define XB_SPIN(cond, bar) do { unsigned _sp = 0; while (cond) { __builtin_amdgcn_s_sleep(1); \
;     if ((++_sp & 255u) == 0u) { if (xb_ld(&(bar)[XB_TMO])) break; if (_sp > XB_SPIN_CAP) { atomicAdd(&(bar)[XB_TMO], 1u); break; } } } } while (0)
; DI void xcd_barrier(const XcdBarrier& b) {
;     ...
;       XB_SPIN(xb_ld(&bar[XB_XGEN(b.x)]) == gen, bar);
.LBB0_78:
	v_readlane_b32 s12, v251, 55
	v_readlane_b32 s13, v251, 56
	s_add_i32 s3, s3, 1
	s_mov_b64 s[14:15], -1
	s_nop 2
	global_load_dword v2, v0, s[12:13] sc1
	s_waitcnt vmcnt(0)
	v_cmp_ge_u32_e32 vcc, v2, v4
	s_orn2_b64 s[12:13], vcc, exec
	s_branch .LBB0_75

; DI unsigned xb_ld(unsigned* p) { return __hip_atomic_load(p, __ATOMIC_RELAXED, __HIP_MEMORY_SCOPE_AGENT); }
; DI unsigned xb_add(unsigned* p, unsigned v) { return __hip_atomic_fetch_add(p, v, __ATOMIC_RELAXED, __HIP_MEMORY_SCOPE_AGENT); }
; #define XB_SPIN(cond, bar) do { unsigned _sp = 0; while (cond) { __builtin_amdgcn_s_sleep(1); \
;     if ((++_sp & 255u) == 0u) { if (xb_ld(&(bar)[XB_TMO])) break; if (_sp > XB_SPIN_CAP) { atomicAdd(&(bar)[XB_TMO], 1u); break; } } } } while (0)
; DI void xcd_barrier(const XcdBarrier& b) {
;     ...
;       const unsigned og = xb_add(&bar[XB_TOP], 1u);
;       const unsigned tg = og / nx;
;       if (og + 1u == (tg + 1u) * nx) xb_add(&bar[XB_TOPGEN], 1u);
;       else XB_SPIN(xb_ld(&bar[XB_TOPGEN]) == tg, bar);
;       __builtin_amdgcn_fence(__ATOMIC_ACQUIRE, "agent");
.LBB0_89:
	s_or_b64 exec, exec, s[6:7]
	v_cvt_f32_u32_e32 v3, v0
	s_waitcnt vmcnt(0)
	v_readfirstlane_b32 s3, v2
	s_mov_b64 s[6:7], -1
	v_rcp_iflag_f32_e32 v3, v3
	v_add_u32_e32 v1, s3, v1
	v_add_u32_e32 v4, 1, v1
	v_mul_f32_e32 v2, 0x4f7ffffe, v3
	v_cvt_u32_f32_e32 v2, v2
	v_sub_u32_e32 v3, 0, v0
	v_mul_lo_u32 v3, v3, v2
	v_mul_hi_u32 v3, v2, v3
	v_add_u32_e32 v2, v2, v3
	v_mul_hi_u32 v2, v1, v2
	v_mul_lo_u32 v3, v2, v0
	v_sub_u32_e32 v1, v1, v3
	v_add_u32_e32 v5, 1, v2
	v_cmp_ge_u32_e32 vcc, v1, v0
	v_sub_u32_e32 v3, v1, v0
	s_nop 0
	v_cndmask_b32_e32 v2, v2, v5, vcc
	v_cndmask_b32_e32 v1, v1, v3, vcc
	v_add_u32_e32 v3, 1, v2
	v_cmp_ge_u32_e32 vcc, v1, v0
	s_nop 1
	v_cndmask_b32_e32 v2, v2, v3, vcc
	v_mad_u64_u32 v[0:1], s[4:5], v0, v2, v[0:1]
	v_readlane_b32 s4, v251, 57
	v_readlane_b32 s5, v251, 58
	v_cmp_ne_u32_e32 vcc, v4, v0
	v_mov_b32_e32 v5, v0
	s_nop 0
	v_mov_b64_e32 v[0:1], s[4:5]
	s_and_saveexec_b64 s[4:5], vcc
	s_cbranch_execz .LBB0_101
	v_readlane_b32 s6, v251, 55
	v_mov_b32_e32 v0, 0
	v_readlane_b32 s7, v251, 56
	s_mov_b64 s[8:9], 0
	s_nop 3
	global_load_dword v1, v0, s[6:7] sc1
	s_waitcnt vmcnt(0)
	v_cmp_lt_u32_e32 vcc, v1, v5
	s_and_saveexec_b64 s[6:7], vcc
	s_cbranch_execz .LBB0_100
	s_mov_b32 s3, 1
	s_branch .LBB0_93

; DI unsigned xb_ld(unsigned* p) { return __hip_atomic_load(p, __ATOMIC_RELAXED, __HIP_MEMORY_SCOPE_AGENT); }
; #define XB_SPIN(cond, bar) do { unsigned _sp = 0; while (cond) { __builtin_amdgcn_s_sleep(1); \
;     if ((++_sp & 255u) == 0u) { if (xb_ld(&(bar)[XB_TMO])) break; if (_sp > XB_SPIN_CAP) { atomicAdd(&(bar)[XB_TMO], 1u); break; } } } } while (0)
; DI void xcd_barrier(const XcdBarrier& b) {
;     ...
;       else XB_SPIN(xb_ld(&bar[XB_TOPGEN]) == tg, bar);
.LBB0_95:
	v_readlane_b32 s12, v251, 55
	v_readlane_b32 s13, v251, 56
	s_add_i32 s3, s3, 1
	s_nop 3
	global_load_dword v1, v0, s[12:13] sc1
	s_mov_b64 s[12:13], -1
	s_waitcnt vmcnt(0)
	v_cmp_ge_u32_e32 vcc, v1, v5
	s_orn2_b64 s[16:17], vcc, exec
	s_branch .LBB0_92

; DI unsigned xb_ld(unsigned* p) { return __hip_atomic_load(p, __ATOMIC_RELAXED, __HIP_MEMORY_SCOPE_AGENT); }
; DI unsigned xb_add(unsigned* p, unsigned v) { return __hip_atomic_fetch_add(p, v, __ATOMIC_RELAXED, __HIP_MEMORY_SCOPE_AGENT); }
; #define XB_SPIN(cond, bar) do { unsigned _sp = 0; while (cond) { __builtin_amdgcn_s_sleep(1); \
;     if ((++_sp & 255u) == 0u) { if (xb_ld(&(bar)[XB_TMO])) break; if (_sp > XB_SPIN_CAP) { atomicAdd(&(bar)[XB_TMO], 1u); break; } } } } while (0)
; DI void xcd_barrier(const XcdBarrier& b) {
;     ...
;     const unsigned old = xb_add(&bar[XB_XSUB(b.x)], 1u);
;     const unsigned gen = old / nloc;
;     if (old + 1u == (gen + 1u) * nloc) {
;       __builtin_amdgcn_fence(__ATOMIC_RELEASE, "agent");
;       asm volatile("s_waitcnt vmcnt(0)" ::: "memory");
;       const unsigned og = xb_add(&bar[XB_TOP], 1u);
;       const unsigned tg = og / nx;
;       if (og + 1u == (tg + 1u) * nx) xb_add(&bar[XB_TOPGEN], 1u);
;       else XB_SPIN(xb_ld(&bar[XB_TOPGEN]) == tg, bar);
;       __builtin_amdgcn_fence(__ATOMIC_ACQUIRE, "agent");
;       xb_add(&bar[XB_XGEN(b.x)], 1u);
;       asm volatile("s_waitcnt vmcnt(0)" ::: "memory");
;     } else {
;       XB_SPIN(xb_ld(&bar[XB_XGEN(b.x)]) == gen, bar);
.LBB0_159:
	s_or_b64 exec, exec, s[2:3]
	s_waitcnt vmcnt(0)
	v_readfirstlane_b32 s2, v4
	v_sub_u32_e32 v5, 0, v2
	s_nop 0
	v_add_u32_e32 v4, s2, v3
	v_cvt_f32_u32_e32 v3, v2
	v_rcp_iflag_f32_e32 v3, v3
	s_nop 0
	v_mul_f32_e32 v3, 0x4f7ffffe, v3
	v_cvt_u32_f32_e32 v3, v3
	v_mul_lo_u32 v5, v5, v3
	v_mul_hi_u32 v5, v3, v5
	v_add_u32_e32 v3, v3, v5
	v_mul_hi_u32 v3, v4, v3
	v_mul_lo_u32 v5, v3, v2
	v_sub_u32_e32 v5, v4, v5
	v_cmp_ge_u32_e32 vcc, v5, v2
	v_add_u32_e32 v6, 1, v3
	s_nop 0
	v_cndmask_b32_e32 v3, v3, v6, vcc
	v_sub_u32_e32 v6, v5, v2
	v_cndmask_b32_e32 v5, v5, v6, vcc
	v_cmp_ge_u32_e32 vcc, v5, v2
	v_add_u32_e32 v5, 1, v3
	v_add_u32_e32 v6, 1, v4
	v_cndmask_b32_e32 v3, v3, v5, vcc
	v_mad_u64_u32 v[4:5], s[2:3], v2, v3, v[2:3]
	v_cmp_ne_u32_e32 vcc, v6, v4
	s_and_saveexec_b64 s[2:3], vcc
	s_xor_b64 s[2:3], exec, s[2:3]
	s_cbranch_execz .LBB0_173
	v_readlane_b32 s4, v251, 55
	v_readlane_b32 s5, v251, 56
	s_waitcnt lgkmcnt(0)
	v_mad_u32_u24 v4, v3, v0, v0
	s_nop 3
	global_load_dword v0, v1, s[4:5] sc1
	s_waitcnt vmcnt(0)
	v_cmp_lt_u32_e32 vcc, v0, v4
	s_and_saveexec_b64 s[4:5], vcc
	s_cbranch_execz .LBB0_172
	s_mov_b32 s38, 1
	s_mov_b64 s[6:7], 0
	s_branch .LBB0_163

; DI unsigned xb_ld(unsigned* p) { return __hip_atomic_load(p, __ATOMIC_RELAXED, __HIP_MEMORY_SCOPE_AGENT); }
; #define XB_SPIN(cond, bar) do { unsigned _sp = 0; while (cond) { __builtin_amdgcn_s_sleep(1); \
;     if ((++_sp & 255u) == 0u) { if (xb_ld(&(bar)[XB_TMO])) break; if (_sp > XB_SPIN_CAP) { atomicAdd(&(bar)[XB_TMO], 1u); break; } } } } while (0)
; DI void xcd_barrier(const XcdBarrier& b) {
;     ...
;       XB_SPIN(xb_ld(&bar[XB_XGEN(b.x)]) == gen, bar);
.LBB0_165:
	v_readlane_b32 s12, v251, 55
	v_readlane_b32 s13, v251, 56
	s_add_i32 s38, s38, 1
	s_mov_b64 s[20:21], -1
	s_nop 2
	global_load_dword v0, v1, s[12:13] sc1
	s_waitcnt vmcnt(0)
	v_cmp_ge_u32_e32 vcc, v0, v4
	s_orn2_b64 s[18:19], vcc, exec
	s_branch .LBB0_162

; DI unsigned xb_ld(unsigned* p) { return __hip_atomic_load(p, __ATOMIC_RELAXED, __HIP_MEMORY_SCOPE_AGENT); }
; DI unsigned xb_add(unsigned* p, unsigned v) { return __hip_atomic_fetch_add(p, v, __ATOMIC_RELAXED, __HIP_MEMORY_SCOPE_AGENT); }
; #define XB_SPIN(cond, bar) do { unsigned _sp = 0; while (cond) { __builtin_amdgcn_s_sleep(1); \
;     if ((++_sp & 255u) == 0u) { if (xb_ld(&(bar)[XB_TMO])) break; if (_sp > XB_SPIN_CAP) { atomicAdd(&(bar)[XB_TMO], 1u); break; } } } } while (0)
; DI void xcd_barrier(const XcdBarrier& b) {
;     ...
;       const unsigned og = xb_add(&bar[XB_TOP], 1u);
;       const unsigned tg = og / nx;
;       if (og + 1u == (tg + 1u) * nx) xb_add(&bar[XB_TOPGEN], 1u);
;       else XB_SPIN(xb_ld(&bar[XB_TOPGEN]) == tg, bar);
;       __builtin_amdgcn_fence(__ATOMIC_ACQUIRE, "agent");
.LBB0_176:
	s_or_b64 exec, exec, s[4:5]
	s_waitcnt vmcnt(0)
	v_readfirstlane_b32 s2, v3
	v_cvt_f32_u32_e32 v3, v0
	v_sub_u32_e32 v4, 0, v0
	v_add_u32_e32 v2, s2, v2
	s_mov_b64 s[4:5], -1
	v_rcp_iflag_f32_e32 v3, v3
	s_nop 0
	v_mul_f32_e32 v3, 0x4f7ffffe, v3
	v_cvt_u32_f32_e32 v3, v3
	v_mul_lo_u32 v4, v4, v3
	v_mul_hi_u32 v4, v3, v4
	v_add_u32_e32 v3, v3, v4
	v_mul_hi_u32 v3, v2, v3
	v_mul_lo_u32 v4, v3, v0
	v_sub_u32_e32 v4, v2, v4
	v_cmp_ge_u32_e32 vcc, v4, v0
	v_add_u32_e32 v5, 1, v3
	s_nop 0
	v_cndmask_b32_e32 v3, v3, v5, vcc
	v_sub_u32_e32 v5, v4, v0
	v_cndmask_b32_e32 v4, v4, v5, vcc
	v_cmp_ge_u32_e32 vcc, v4, v0
	v_add_u32_e32 v4, 1, v3
	v_add_u32_e32 v5, 1, v2
	v_cndmask_b32_e32 v4, v3, v4, vcc
	v_mad_u64_u32 v[2:3], s[2:3], v0, v4, v[0:1]
	v_readlane_b32 s2, v251, 57
	v_readlane_b32 s3, v251, 58
	v_cmp_ne_u32_e32 vcc, v5, v2
	v_mov_b32_e32 v5, v2
	s_nop 0
	v_mov_b64_e32 v[2:3], s[2:3]
	s_and_saveexec_b64 s[2:3], vcc
	s_cbranch_execz .LBB0_188
	v_readlane_b32 s4, v251, 55
	v_readlane_b32 s5, v251, 56
	s_mov_b64 s[6:7], 0
	s_nop 3
	global_load_dword v0, v1, s[4:5] sc1
	s_waitcnt vmcnt(0)
	v_cmp_lt_u32_e32 vcc, v0, v5
	s_and_saveexec_b64 s[4:5], vcc
	s_cbranch_execz .LBB0_187
	s_mov_b32 s38, 1
	s_branch .LBB0_180

; DI unsigned xb_ld(unsigned* p) { return __hip_atomic_load(p, __ATOMIC_RELAXED, __HIP_MEMORY_SCOPE_AGENT); }
; #define XB_SPIN(cond, bar) do { unsigned _sp = 0; while (cond) { __builtin_amdgcn_s_sleep(1); \
;     if ((++_sp & 255u) == 0u) { if (xb_ld(&(bar)[XB_TMO])) break; if (_sp > XB_SPIN_CAP) { atomicAdd(&(bar)[XB_TMO], 1u); break; } } } } while (0)
; DI void xcd_barrier(const XcdBarrier& b) {
;     ...
;       else XB_SPIN(xb_ld(&bar[XB_TOPGEN]) == tg, bar);
.LBB0_182:
	v_readlane_b32 s12, v251, 55
	v_readlane_b32 s13, v251, 56
	s_add_i32 s38, s38, 1
	s_mov_b64 s[20:21], -1
	s_nop 2
	global_load_dword v0, v1, s[12:13] sc1
	s_waitcnt vmcnt(0)
	v_cmp_ge_u32_e32 vcc, v0, v5
	s_orn2_b64 s[18:19], vcc, exec
	s_branch .LBB0_179

; DI unsigned xb_ld(unsigned* p) { return __hip_atomic_load(p, __ATOMIC_RELAXED, __HIP_MEMORY_SCOPE_AGENT); }
; DI unsigned xb_add(unsigned* p, unsigned v) { return __hip_atomic_fetch_add(p, v, __ATOMIC_RELAXED, __HIP_MEMORY_SCOPE_AGENT); }
; #define XB_SPIN(cond, bar) do { unsigned _sp = 0; while (cond) { __builtin_amdgcn_s_sleep(1); \
;     if ((++_sp & 255u) == 0u) { if (xb_ld(&(bar)[XB_TMO])) break; if (_sp > XB_SPIN_CAP) { atomicAdd(&(bar)[XB_TMO], 1u); break; } } } } while (0)
; DI void xcd_barrier(const XcdBarrier& b) {
;     ...
;     const unsigned old = xb_add(&bar[XB_XSUB(b.x)], 1u);
;     const unsigned gen = old / nloc;
;     if (old + 1u == (gen + 1u) * nloc) {
;       __builtin_amdgcn_fence(__ATOMIC_RELEASE, "agent");
;       asm volatile("s_waitcnt vmcnt(0)" ::: "memory");
;       const unsigned og = xb_add(&bar[XB_TOP], 1u);
;       const unsigned tg = og / nx;
;       if (og + 1u == (tg + 1u) * nx) xb_add(&bar[XB_TOPGEN], 1u);
;       else XB_SPIN(xb_ld(&bar[XB_TOPGEN]) == tg, bar);
.LBB0_358:
	s_or_b64 exec, exec, s[2:3]
	s_waitcnt vmcnt(0)
	v_readfirstlane_b32 s2, v4
	v_sub_u32_e32 v5, 0, v2
	s_nop 0
	v_add_u32_e32 v4, s2, v3
	v_cvt_f32_u32_e32 v3, v2
	v_rcp_iflag_f32_e32 v3, v3
	s_nop 0
	v_mul_f32_e32 v3, 0x4f7ffffe, v3
	v_cvt_u32_f32_e32 v3, v3
	v_mul_lo_u32 v5, v5, v3
	v_mul_hi_u32 v5, v3, v5
	v_add_u32_e32 v3, v3, v5
	v_mul_hi_u32 v3, v4, v3
	v_mul_lo_u32 v5, v3, v2
	v_sub_u32_e32 v5, v4, v5
	v_cmp_ge_u32_e32 vcc, v5, v2
	v_add_u32_e32 v6, 1, v3
	s_nop 0
	v_cndmask_b32_e32 v3, v3, v6, vcc
	v_sub_u32_e32 v6, v5, v2
	v_cndmask_b32_e32 v5, v5, v6, vcc
	v_cmp_ge_u32_e32 vcc, v5, v2
	v_add_u32_e32 v5, 1, v3
	v_add_u32_e32 v6, 1, v4
	v_cndmask_b32_e32 v3, v3, v5, vcc
	v_mad_u64_u32 v[4:5], s[2:3], v2, v3, v[2:3]
	v_cmp_ne_u32_e32 vcc, v6, v4
	s_and_saveexec_b64 s[2:3], vcc
	s_xor_b64 s[2:3], exec, s[2:3]
	s_cbranch_execz .LBB0_372
	v_readlane_b32 s4, v251, 55
	v_readlane_b32 s5, v251, 56
	s_waitcnt lgkmcnt(0)
	v_mad_u32_u24 v4, v3, v0, v0
	s_nop 3
	global_load_dword v0, v1, s[4:5] sc1
	s_waitcnt vmcnt(0)
	v_cmp_lt_u32_e32 vcc, v0, v4
	s_and_saveexec_b64 s[4:5], vcc
	s_cbranch_execz .LBB0_371
	s_mov_b32 s40, 1
	s_mov_b64 s[6:7], 0
	s_branch .LBB0_362

; DI unsigned xb_ld(unsigned* p) { return __hip_atomic_load(p, __ATOMIC_RELAXED, __HIP_MEMORY_SCOPE_AGENT); }
; #define XB_SPIN(cond, bar) do { unsigned _sp = 0; while (cond) { __builtin_amdgcn_s_sleep(1); \
;     if ((++_sp & 255u) == 0u) { if (xb_ld(&(bar)[XB_TMO])) break; if (_sp > XB_SPIN_CAP) { atomicAdd(&(bar)[XB_TMO], 1u); break; } } } } while (0)
; DI void xcd_barrier(const XcdBarrier& b) {
;     ...
;       else XB_SPIN(xb_ld(&bar[XB_TOPGEN]) == tg, bar);
.LBB0_364:
	v_readlane_b32 s18, v251, 55
	v_readlane_b32 s19, v251, 56
	s_add_i32 s40, s40, 1
	s_mov_b64 s[36:37], -1
	s_nop 2
	global_load_dword v0, v1, s[18:19] sc1
	s_waitcnt vmcnt(0)
	v_cmp_ge_u32_e32 vcc, v0, v4
	s_orn2_b64 s[18:19], vcc, exec
	s_branch .LBB0_361

; DI unsigned xb_ld(unsigned* p) { return __hip_atomic_load(p, __ATOMIC_RELAXED, __HIP_MEMORY_SCOPE_AGENT); }
; DI unsigned xb_add(unsigned* p, unsigned v) { return __hip_atomic_fetch_add(p, v, __ATOMIC_RELAXED, __HIP_MEMORY_SCOPE_AGENT); }
; #define XB_SPIN(cond, bar) do { unsigned _sp = 0; while (cond) { __builtin_amdgcn_s_sleep(1); \
;     if ((++_sp & 255u) == 0u) { if (xb_ld(&(bar)[XB_TMO])) break; if (_sp > XB_SPIN_CAP) { atomicAdd(&(bar)[XB_TMO], 1u); break; } } } } while (0)
; DI void xcd_barrier(const XcdBarrier& b) {
;     ...
;     const unsigned old = xb_add(&bar[XB_XSUB(b.x)], 1u);
;     const unsigned gen = old / nloc;
;     if (old + 1u == (gen + 1u) * nloc) {
;       __builtin_amdgcn_fence(__ATOMIC_RELEASE, "agent");
;       asm volatile("s_waitcnt vmcnt(0)" ::: "memory");
;       const unsigned og = xb_add(&bar[XB_TOP], 1u);
;       const unsigned tg = og / nx;
;       if (og + 1u == (tg + 1u) * nx) xb_add(&bar[XB_TOPGEN], 1u);
;       else XB_SPIN(xb_ld(&bar[XB_TOPGEN]) == tg, bar);
.LBB0_375:
	s_or_b64 exec, exec, s[4:5]
	s_waitcnt vmcnt(0)
	v_readfirstlane_b32 s2, v3
	v_cvt_f32_u32_e32 v3, v0
	v_sub_u32_e32 v4, 0, v0
	v_add_u32_e32 v2, s2, v2
	s_mov_b64 s[4:5], -1
	v_rcp_iflag_f32_e32 v3, v3
	s_nop 0
	v_mul_f32_e32 v3, 0x4f7ffffe, v3
	v_cvt_u32_f32_e32 v3, v3
	v_mul_lo_u32 v4, v4, v3
	v_mul_hi_u32 v4, v3, v4
	v_add_u32_e32 v3, v3, v4
	v_mul_hi_u32 v3, v2, v3
	v_mul_lo_u32 v4, v3, v0
	v_sub_u32_e32 v4, v2, v4
	v_cmp_ge_u32_e32 vcc, v4, v0
	v_add_u32_e32 v5, 1, v3
	s_nop 0
	v_cndmask_b32_e32 v3, v3, v5, vcc
	v_sub_u32_e32 v5, v4, v0
	v_cndmask_b32_e32 v4, v4, v5, vcc
	v_cmp_ge_u32_e32 vcc, v4, v0
	v_add_u32_e32 v4, 1, v3
	v_add_u32_e32 v5, 1, v2
	v_cndmask_b32_e32 v4, v3, v4, vcc
	v_mad_u64_u32 v[2:3], s[2:3], v0, v4, v[0:1]
	v_readlane_b32 s2, v251, 57
	v_readlane_b32 s3, v251, 58
	v_cmp_ne_u32_e32 vcc, v5, v2
	v_mov_b32_e32 v5, v2
	s_nop 0
	v_mov_b64_e32 v[2:3], s[2:3]
	s_and_saveexec_b64 s[2:3], vcc
	s_cbranch_execz .LBB0_387
	v_readlane_b32 s4, v251, 55
	v_readlane_b32 s5, v251, 56
	s_mov_b64 s[6:7], 0
	s_nop 3
	global_load_dword v0, v1, s[4:5] sc1
	s_waitcnt vmcnt(0)
	v_cmp_lt_u32_e32 vcc, v0, v5
	s_and_saveexec_b64 s[4:5], vcc
	s_cbranch_execz .LBB0_386
	s_mov_b32 s40, 1
	s_branch .LBB0_379

; DI unsigned xb_ld(unsigned* p) { return __hip_atomic_load(p, __ATOMIC_RELAXED, __HIP_MEMORY_SCOPE_AGENT); }
; #define XB_SPIN(cond, bar) do { unsigned _sp = 0; while (cond) { __builtin_amdgcn_s_sleep(1); \
;     if ((++_sp & 255u) == 0u) { if (xb_ld(&(bar)[XB_TMO])) break; if (_sp > XB_SPIN_CAP) { atomicAdd(&(bar)[XB_TMO], 1u); break; } } } } while (0)
; DI void xcd_barrier(const XcdBarrier& b) {
;     ...
;       else XB_SPIN(xb_ld(&bar[XB_TOPGEN]) == tg, bar);
.LBB0_381:
	v_readlane_b32 s18, v251, 55
	v_readlane_b32 s19, v251, 56
	s_add_i32 s40, s40, 1
	s_mov_b64 s[36:37], -1
	s_nop 2
	global_load_dword v0, v1, s[18:19] sc1
	s_waitcnt vmcnt(0)
	v_cmp_ge_u32_e32 vcc, v0, v5
	s_orn2_b64 s[18:19], vcc, exec
	s_branch .LBB0_378

; DI unsigned xb_ld(unsigned* p) { return __hip_atomic_load(p, __ATOMIC_RELAXED, __HIP_MEMORY_SCOPE_AGENT); }
; #define XB_SPIN(cond, bar) do { unsigned _sp = 0; while (cond) { __builtin_amdgcn_s_sleep(1); \
;     if ((++_sp & 255u) == 0u) { if (xb_ld(&(bar)[XB_TMO])) break; if (_sp > XB_SPIN_CAP) { atomicAdd(&(bar)[XB_TMO], 1u); break; } } } } while (0)
; DI void xcd_barrier(const XcdBarrier& b) {
;     ...
;       else XB_SPIN(xb_ld(&bar[XB_TOPGEN]) == tg, bar);
.LBB0_495:
	v_readlane_b32 s18, v251, 55
	v_readlane_b32 s19, v251, 56
	s_add_i32 s38, s38, 1
	s_mov_b64 s[34:35], -1
	s_nop 2
	global_load_dword v0, v1, s[18:19] sc1
	s_waitcnt vmcnt(0)
	v_cmp_ge_u32_e32 vcc, v0, v4
	s_orn2_b64 s[18:19], vcc, exec
	s_branch .LBB0_492

; DI unsigned xb_ld(unsigned* p) { return __hip_atomic_load(p, __ATOMIC_RELAXED, __HIP_MEMORY_SCOPE_AGENT); }
; #define XB_SPIN(cond, bar) do { unsigned _sp = 0; while (cond) { __builtin_amdgcn_s_sleep(1); \
;     if ((++_sp & 255u) == 0u) { if (xb_ld(&(bar)[XB_TMO])) break; if (_sp > XB_SPIN_CAP) { atomicAdd(&(bar)[XB_TMO], 1u); break; } } } } while (0)
; DI void xcd_barrier(const XcdBarrier& b) {
;     ...
;       else XB_SPIN(xb_ld(&bar[XB_TOPGEN]) == tg, bar);
.LBB0_512:
	v_readlane_b32 s18, v251, 55
	v_readlane_b32 s19, v251, 56
	s_add_i32 s38, s38, 1
	s_mov_b64 s[34:35], -1
	s_nop 2
	global_load_dword v0, v1, s[18:19] sc1
	s_waitcnt vmcnt(0)
	v_cmp_ge_u32_e32 vcc, v0, v5
	s_orn2_b64 s[18:19], vcc, exec
	s_branch .LBB0_509
